# pass A state stores: 32 global_store_short per lane replaced by LDS transpose + 4 dwordx4 stores per wave
# speedup vs baseline: 1.0242x; 1.0076x over previous
.LBB0_201:
	s_or_b64 exec, exec, s[4:5]
	v_bfe_u32 v31, v36, 5, 1
	v_and_b32_e32 v34, 31, v36
	s_ashr_i32 s0, s26, 7
	v_lshl_or_b32 v0, s0, 5, v34
	v_lshl_add_u32 v30, v31, 4, 0
	v_mad_u64_u32 v[26:27], s[4:5], v0, s24, v[30:31]
	s_waitcnt lgkmcnt(0)
	s_barrier
	ds_read_b128 v[18:21], v26 offset:35072
	s_and_b32 s4, s26, 64
	v_or_b32_e32 v37, s4, v34
	v_mad_u32_u24 v27, v37, s24, v30
	ds_read_b128 v[0:3], v27 offset:53504
	ds_read_b128 v[38:41], v26 offset:35104
	ds_read_b128 v[22:25], v27 offset:53536
	s_waitcnt lgkmcnt(2)
	v_mfma_f32_32x32x16_bf16 v[0:15], v[18:21], v[0:3], 0
	ds_read_b128 v[42:45], v26 offset:35136
	v_bfe_u32 v28, v36, 3, 1
	v_lshl_or_b32 v47, s0, 4, v28
	s_lshl_b32 s0, s4, 2
	s_add_i32 s0, s0, 0
	v_lshlrev_b64 v[16:17], 15, v[16:17]
	v_lshl_add_u64 v[16:17], s[88:89], 0, v[16:17]
	s_waitcnt lgkmcnt(1)
	v_mfma_f32_32x32x16_bf16 v[0:15], v[38:41], v[22:25], v[0:15]
	ds_read_b128 v[22:25], v27 offset:53568
	ds_read_b128 v[48:51], v26 offset:35168
	ds_read_b128 v[26:29], v27 offset:53600
	s_add_i32 s25, s25, 1
	s_cmp_lg_u32 s25, s20
	s_waitcnt lgkmcnt(2)
	v_mfma_f32_32x32x16_bf16 v[0:15], v[42:45], v[22:25], v[0:15]
	v_lshl_add_u32 v22, v34, 2, s0
	v_add_u32_e32 v23, 0x7c00, v22
	v_add_u32_e32 v22, 0x3c00, v22
	ds_read2_b32 v[52:53], v23 offset0:191 offset1:223
	ds_read2_b32 v[54:55], v22 offset0:159 offset1:191
	v_and_b32_e32 v22, 7, v36
	v_lshlrev_b32_e32 v34, 1, v22
	s_waitcnt lgkmcnt(2)
	v_mfma_f32_32x32x16_bf16 v[0:15], v[48:51], v[26:29], v[0:15]
	v_lshl_add_u64 v[56:57], v[16:17], 0, v[34:35]
	s_waitcnt lgkmcnt(0)
	v_sub_f32_e32 v16, v52, v54
	v_mul_f32_e32 v16, 0x3fb8aa3b, v16
	v_exp_f32_e32 v52, v16
	v_lshrrev_b32_e32 v16, 3, v37
	v_and_or_b32 v16, v16, 10, v47
	v_lshlrev_b32_e32 v16, 8, v16
	v_ashrrev_i32_e32 v17, 31, v16
	v_lshl_add_u64 v[16:17], v[16:17], 1, v[56:57]
	s_nop 1
	v_mul_f32_e32 v0, v0, v52
	v_lshlrev_b32_e32 v34, 6, v31
	v_cvt_pk_bf16_f32 v0, v0, s0
	v_lshl_add_u64 v[58:59], v[16:17], 0, v[34:35]
	s_nop 0
	v_readfirstlane_b32 s98, v58
	v_readfirstlane_b32 s99, v59
	v_and_b32_e32 v100, 63, v36
	v_and_b32_e32 v101, 7, v100
	v_lshlrev_b32_e32 v101, 1, v101
	v_bfe_u32 v102, v100, 3, 2
	v_lshl_add_u32 v101, v102, 9, v101
	v_bfe_u32 v102, v100, 5, 1
	v_lshl_add_u32 v101, v102, 6, v101
	v_lshrrev_b32_e32 v102, 6, v36
	v_lshlrev_b32_e32 v102, 12, v102
	v_add_u32_e32 v102, 0x12400, v102
	v_add_u32_e32 v101, v102, v101
	v_lshl_add_u32 v103, v100, 4, v102
	v_lshlrev_b32_e32 v102, 4, v100
	ds_write_b16 v101, v0
	v_mul_f32_e32 v0, v1, v52
	v_cvt_pk_bf16_f32 v0, v0, s0
	ds_write_b16 v101, v0 offset:16
	v_mul_f32_e32 v0, v2, v52
	v_cvt_pk_bf16_f32 v0, v0, s0
	ds_write_b16 v101, v0 offset:32
	v_mul_f32_e32 v0, v3, v52
	v_cvt_pk_bf16_f32 v0, v0, s0
	ds_write_b16 v101, v0 offset:48
	v_mul_f32_e32 v0, v4, v52
	v_cvt_pk_bf16_f32 v0, v0, s0
	ds_write_b16 v101, v0 offset:128
	v_mul_f32_e32 v0, v5, v52
	v_cvt_pk_bf16_f32 v0, v0, s0
	ds_write_b16 v101, v0 offset:144
	v_mul_f32_e32 v0, v6, v52
	v_cvt_pk_bf16_f32 v0, v0, s0
	ds_write_b16 v101, v0 offset:160
	v_mul_f32_e32 v0, v7, v52
	v_cvt_pk_bf16_f32 v0, v0, s0
	ds_write_b16 v101, v0 offset:176
	v_mul_f32_e32 v0, v8, v52
	v_or_b32_e32 v8, 32, v37
	v_mad_u32_u24 v37, v8, s24, v30
	v_cvt_pk_bf16_f32 v4, v0, s0
	ds_read_b128 v[0:3], v37 offset:53504
	ds_write_b16 v101, v4 offset:256
	v_mul_f32_e32 v4, v9, v52
	v_cvt_pk_bf16_f32 v9, v4, s0
	ds_read_b128 v[4:7], v37 offset:53536
	s_waitcnt lgkmcnt(1)
	v_mfma_f32_32x32x16_bf16 v[16:31], v[18:21], v[0:3], 0
	v_mul_f32_e32 v0, v10, v52
	v_cvt_pk_bf16_f32 v0, v0, s0
	ds_write_b16 v101, v0 offset:288
	v_mul_f32_e32 v0, v11, v52
	v_cvt_pk_bf16_f32 v0, v0, s0
	ds_write_b16 v101, v0 offset:304
	v_mul_f32_e32 v0, v12, v52
	s_waitcnt lgkmcnt(0)
	v_mfma_f32_32x32x16_bf16 v[16:31], v[38:41], v[4:7], v[16:31]
	v_cvt_pk_bf16_f32 v4, v0, s0
	ds_read_b128 v[0:3], v37 offset:53568
	ds_write_b16 v101, v4 offset:384
	v_mul_f32_e32 v4, v13, v52
	ds_write_b16 v101, v9 offset:272
	v_cvt_pk_bf16_f32 v9, v4, s0
	ds_read_b128 v[4:7], v37 offset:53600
	s_waitcnt lgkmcnt(1)
	v_mfma_f32_32x32x16_bf16 v[16:31], v[42:45], v[0:3], v[16:31]
	v_mul_f32_e32 v0, v14, v52
	v_cvt_pk_bf16_f32 v0, v0, s0
	ds_write_b16 v101, v0 offset:416
	v_mul_f32_e32 v0, v15, v52
	v_cvt_pk_bf16_f32 v0, v0, s0
	ds_write_b16 v101, v0 offset:432
	v_sub_f32_e32 v0, v53, v55
	s_waitcnt lgkmcnt(0)
	v_mfma_f32_32x32x16_bf16 v[16:31], v[48:51], v[4:7], v[16:31]
	v_mul_f32_e32 v0, 0x3fb8aa3b, v0
	v_exp_f32_e32 v2, v0
	v_lshrrev_b32_e32 v0, 3, v8
	v_and_or_b32 v0, v0, 14, v47
	v_lshlrev_b32_e32 v0, 8, v0
	v_ashrrev_i32_e32 v1, 31, v0
	v_lshl_add_u64 v[0:1], v[0:1], 1, v[56:57]
	s_nop 4
	v_mul_f32_e32 v3, v16, v2
	v_cvt_pk_bf16_f32 v3, v3, s0
	v_lshl_add_u64 v[0:1], v[0:1], 0, v[34:35]
	s_nop 0
	v_readfirstlane_b32 s100, v0
	v_readfirstlane_b32 s101, v1
	ds_write_b16 v101, v3 offset:2048
	v_mul_f32_e32 v3, v17, v2
	v_cvt_pk_bf16_f32 v3, v3, s0
	ds_write_b16 v101, v3 offset:2064
	v_mul_f32_e32 v3, v18, v2
	v_cvt_pk_bf16_f32 v3, v3, s0
	ds_write_b16 v101, v3 offset:2080
	v_mul_f32_e32 v3, v19, v2
	v_cvt_pk_bf16_f32 v3, v3, s0
	ds_write_b16 v101, v3 offset:2096
	v_mul_f32_e32 v3, v20, v2
	v_cvt_pk_bf16_f32 v3, v3, s0
	ds_write_b16 v101, v3 offset:2176
	v_mul_f32_e32 v3, v21, v2
	v_cvt_pk_bf16_f32 v3, v3, s0
	ds_write_b16 v101, v3 offset:2192
	v_mul_f32_e32 v3, v22, v2
	v_cvt_pk_bf16_f32 v3, v3, s0
	ds_write_b16 v101, v3 offset:2208
	v_mul_f32_e32 v3, v23, v2
	v_cvt_pk_bf16_f32 v3, v3, s0
	ds_write_b16 v101, v3 offset:2224
	v_mul_f32_e32 v3, v24, v2
	v_cvt_pk_bf16_f32 v3, v3, s0
	ds_write_b16 v101, v3 offset:2304
	v_mul_f32_e32 v3, v25, v2
	v_cvt_pk_bf16_f32 v3, v3, s0
	ds_write_b16 v101, v3 offset:2320
	v_mul_f32_e32 v3, v26, v2
	v_cvt_pk_bf16_f32 v3, v3, s0
	ds_write_b16 v101, v3 offset:2336
	v_mul_f32_e32 v3, v27, v2
	v_cvt_pk_bf16_f32 v3, v3, s0
	ds_write_b16 v101, v3 offset:2352
	v_mul_f32_e32 v3, v28, v2
	v_cvt_pk_bf16_f32 v3, v3, s0
	ds_write_b16 v101, v3 offset:2432
	v_mul_f32_e32 v3, v29, v2
	v_cvt_pk_bf16_f32 v3, v3, s0
	ds_write_b16 v101, v3 offset:2448
	v_mul_f32_e32 v3, v30, v2
	v_mul_f32_e32 v2, v31, v2
	v_cvt_pk_bf16_f32 v3, v3, s0
	v_cvt_pk_bf16_f32 v2, v2, s0
	ds_write_b16 v101, v3 offset:2464
	ds_write_b16 v101, v2 offset:2480
	v_lshlrev_b32_e32 v0, 5, v36
	v_and_b32_e32 v12, 0xe0, v0
	v_lshlrev_b32_e32 v0, 4, v36
	v_and_b32_e32 v0, 0x70, v0
	v_add_u32_e32 v4, 0, v0
	v_ashrrev_i32_e32 v0, 3, v36
	v_and_b32_e32 v5, 0x78, v36
	v_and_b32_e32 v1, 0xffffff00, v36
	v_and_b32_e32 v2, 16, v0
	v_or3_b32 v6, v2, v1, v12
	v_mad_u64_u32 v[0:1], s[4:5], v0, s24, v[4:5]
	ds_write_b16 v101, v9 offset:400
	ds_read_b128 v[104:107], v103
	ds_read_b128 v[108:111], v103 offset:1024
	ds_read_b128 v[112:115], v103 offset:2048
	ds_read_b128 v[116:119], v103 offset:3072
	s_waitcnt lgkmcnt(0)
	global_store_dwordx4 v102, v[104:107], s[98:99]
	global_store_dwordx4 v102, v[108:111], s[98:99] offset:1024
	global_store_dwordx4 v102, v[112:115], s[100:101]
	global_store_dwordx4 v102, v[116:119], s[100:101] offset:1024
	ds_read_b128 v[0:3], v0 offset:35072
	v_ashrrev_i32_e32 v6, 4, v6
	v_mov_b64_e32 v[8:9], s[2:3]
	v_mad_i64_i32 v[6:7], s[2:3], v6, s9, v[8:9]
	v_lshlrev_b32_e32 v34, 1, v5
	v_lshl_add_u64 v[6:7], v[6:7], 0, v[34:35]
	v_add_u32_e32 v13, 0x200, v36
	v_add_co_u32_e32 v10, vcc, s10, v6
	v_ashrrev_i32_e32 v14, 3, v13
	s_nop 0
	v_addc_co_u32_e32 v11, vcc, 0, v7, vcc
	v_mad_u64_u32 v[4:5], s[2:3], v14, s24, v[4:5]
	ds_read_b128 v[4:7], v4 offset:35072
	s_waitcnt lgkmcnt(1)
	global_store_dwordx4 v[10:11], v[0:3], off
	s_nop 1
	v_and_b32_e32 v0, 0xffffff00, v13
	v_and_b32_e32 v1, 16, v14
	v_or3_b32 v0, v0, v1, v12
	v_ashrrev_i32_e32 v0, 4, v0
	v_mad_i64_i32 v[0:1], s[2:3], v0, s9, v[8:9]
	v_lshl_add_u64 v[0:1], v[0:1], 0, v[34:35]
	v_add_co_u32_e32 v0, vcc, 0x1000, v0
	s_nop 1
	v_addc_co_u32_e32 v1, vcc, 0, v1, vcc
	s_waitcnt lgkmcnt(0)
	global_store_dwordx4 v[0:1], v[4:7], off
	s_barrier
	s_cbranch_scc0 .LBB0_222

.LBB0_396:
	s_or_b64 exec, exec, s[4:5]
	v_bfe_u32 v31, v36, 5, 1
	v_and_b32_e32 v34, 31, v36
	s_ashr_i32 s6, s26, 7
	v_lshl_or_b32 v0, s6, 5, v34
	v_lshl_add_u32 v30, v31, 4, 0
	v_mad_u64_u32 v[26:27], s[4:5], v0, s24, v[30:31]
	s_waitcnt lgkmcnt(0)
	s_barrier
	ds_read_b128 v[18:21], v26 offset:35072
	s_and_b32 s4, s26, 64
	v_or_b32_e32 v37, s4, v34
	v_mad_u32_u24 v27, v37, s24, v30
	ds_read_b128 v[0:3], v27 offset:53504
	ds_read_b128 v[38:41], v26 offset:35104
	ds_read_b128 v[22:25], v27 offset:53536
	s_waitcnt lgkmcnt(2)
	v_mfma_f32_32x32x16_bf16 v[0:15], v[18:21], v[0:3], 0
	ds_read_b128 v[42:45], v26 offset:35136
	s_lshl_b32 s4, s4, 2
	v_bfe_u32 v28, v36, 3, 1
	s_add_i32 s4, s4, 0
	v_lshl_or_b32 v47, s6, 4, v28
	v_lshlrev_b64 v[16:17], 15, v[16:17]
	v_lshl_add_u64 v[16:17], s[88:89], 0, v[16:17]
	s_waitcnt lgkmcnt(1)
	v_mfma_f32_32x32x16_bf16 v[0:15], v[38:41], v[22:25], v[0:15]
	ds_read_b128 v[22:25], v27 offset:53568
	ds_read_b128 v[48:51], v26 offset:35168
	ds_read_b128 v[26:29], v27 offset:53600
	s_add_i32 s25, s25, 1
	s_cmp_lg_u32 s25, s20
	s_waitcnt lgkmcnt(2)
	v_mfma_f32_32x32x16_bf16 v[0:15], v[42:45], v[22:25], v[0:15]
	v_lshl_add_u32 v22, v34, 2, s4
	v_add_u32_e32 v23, 0x7c00, v22
	v_add_u32_e32 v22, 0x3c00, v22
	ds_read2_b32 v[52:53], v23 offset0:191 offset1:223
	ds_read2_b32 v[54:55], v22 offset0:159 offset1:191
	v_and_b32_e32 v22, 7, v36
	v_lshlrev_b32_e32 v34, 1, v22
	s_waitcnt lgkmcnt(2)
	v_mfma_f32_32x32x16_bf16 v[0:15], v[48:51], v[26:29], v[0:15]
	v_lshl_add_u64 v[56:57], v[16:17], 0, v[34:35]
	s_waitcnt lgkmcnt(0)
	v_sub_f32_e32 v16, v52, v54
	v_mul_f32_e32 v16, 0x3fb8aa3b, v16
	v_exp_f32_e32 v52, v16
	v_lshrrev_b32_e32 v16, 3, v37
	v_and_or_b32 v16, v16, 10, v47
	v_lshlrev_b32_e32 v16, 8, v16
	v_ashrrev_i32_e32 v17, 31, v16
	v_lshl_add_u64 v[16:17], v[16:17], 1, v[56:57]
	s_nop 1
	v_mul_f32_e32 v0, v0, v52
	v_lshlrev_b32_e32 v34, 6, v31
	v_cvt_pk_bf16_f32 v0, v0, s0
	v_lshl_add_u64 v[58:59], v[16:17], 0, v[34:35]
	s_nop 0
	v_readfirstlane_b32 s98, v58
	v_readfirstlane_b32 s99, v59
	v_and_b32_e32 v100, 63, v36
	v_and_b32_e32 v101, 7, v100
	v_lshlrev_b32_e32 v101, 1, v101
	v_bfe_u32 v102, v100, 3, 2
	v_lshl_add_u32 v101, v102, 9, v101
	v_bfe_u32 v102, v100, 5, 1
	v_lshl_add_u32 v101, v102, 6, v101
	v_lshrrev_b32_e32 v102, 6, v36
	v_lshlrev_b32_e32 v102, 12, v102
	v_add_u32_e32 v102, 0x12400, v102
	v_add_u32_e32 v101, v102, v101
	v_lshl_add_u32 v103, v100, 4, v102
	v_lshlrev_b32_e32 v102, 4, v100
	ds_write_b16 v101, v0
	v_mul_f32_e32 v0, v1, v52
	v_cvt_pk_bf16_f32 v0, v0, s0
	ds_write_b16 v101, v0 offset:16
	v_mul_f32_e32 v0, v2, v52
	v_cvt_pk_bf16_f32 v0, v0, s0
	ds_write_b16 v101, v0 offset:32
	v_mul_f32_e32 v0, v3, v52
	v_cvt_pk_bf16_f32 v0, v0, s0
	ds_write_b16 v101, v0 offset:48
	v_mul_f32_e32 v0, v4, v52
	v_cvt_pk_bf16_f32 v0, v0, s0
	ds_write_b16 v101, v0 offset:128
	v_mul_f32_e32 v0, v5, v52
	v_cvt_pk_bf16_f32 v0, v0, s0
	ds_write_b16 v101, v0 offset:144
	v_mul_f32_e32 v0, v6, v52
	v_cvt_pk_bf16_f32 v0, v0, s0
	ds_write_b16 v101, v0 offset:160
	v_mul_f32_e32 v0, v7, v52
	v_cvt_pk_bf16_f32 v0, v0, s0
	ds_write_b16 v101, v0 offset:176
	v_mul_f32_e32 v0, v8, v52
	v_or_b32_e32 v8, 32, v37
	v_mad_u32_u24 v37, v8, s24, v30
	v_cvt_pk_bf16_f32 v4, v0, s0
	ds_read_b128 v[0:3], v37 offset:53504
	ds_write_b16 v101, v4 offset:256
	v_mul_f32_e32 v4, v9, v52
	v_cvt_pk_bf16_f32 v9, v4, s0
	ds_read_b128 v[4:7], v37 offset:53536
	s_waitcnt lgkmcnt(1)
	v_mfma_f32_32x32x16_bf16 v[16:31], v[18:21], v[0:3], 0
	v_mul_f32_e32 v0, v10, v52
	v_cvt_pk_bf16_f32 v0, v0, s0
	ds_write_b16 v101, v0 offset:288
	v_mul_f32_e32 v0, v11, v52
	v_cvt_pk_bf16_f32 v0, v0, s0
	ds_write_b16 v101, v0 offset:304
	v_mul_f32_e32 v0, v12, v52
	s_waitcnt lgkmcnt(0)
	v_mfma_f32_32x32x16_bf16 v[16:31], v[38:41], v[4:7], v[16:31]
	v_cvt_pk_bf16_f32 v4, v0, s0
	ds_read_b128 v[0:3], v37 offset:53568
	ds_write_b16 v101, v4 offset:384
	v_mul_f32_e32 v4, v13, v52
	ds_write_b16 v101, v9 offset:272
	v_cvt_pk_bf16_f32 v9, v4, s0
	ds_read_b128 v[4:7], v37 offset:53600
	s_waitcnt lgkmcnt(1)
	v_mfma_f32_32x32x16_bf16 v[16:31], v[42:45], v[0:3], v[16:31]
	v_mul_f32_e32 v0, v14, v52
	v_cvt_pk_bf16_f32 v0, v0, s0
	ds_write_b16 v101, v0 offset:416
	v_mul_f32_e32 v0, v15, v52
	v_cvt_pk_bf16_f32 v0, v0, s0
	ds_write_b16 v101, v0 offset:432
	v_sub_f32_e32 v0, v53, v55
	s_waitcnt lgkmcnt(0)
	v_mfma_f32_32x32x16_bf16 v[16:31], v[48:51], v[4:7], v[16:31]
	v_mul_f32_e32 v0, 0x3fb8aa3b, v0
	v_exp_f32_e32 v2, v0
	v_lshrrev_b32_e32 v0, 3, v8
	v_and_or_b32 v0, v0, 14, v47
	v_lshlrev_b32_e32 v0, 8, v0
	v_ashrrev_i32_e32 v1, 31, v0
	v_lshl_add_u64 v[0:1], v[0:1], 1, v[56:57]
	s_nop 4
	v_mul_f32_e32 v3, v16, v2
	v_cvt_pk_bf16_f32 v3, v3, s0
	v_lshl_add_u64 v[0:1], v[0:1], 0, v[34:35]
	s_nop 0
	v_readfirstlane_b32 s100, v0
	v_readfirstlane_b32 s101, v1
	ds_write_b16 v101, v3 offset:2048
	v_mul_f32_e32 v3, v17, v2
	v_cvt_pk_bf16_f32 v3, v3, s0
	ds_write_b16 v101, v3 offset:2064
	v_mul_f32_e32 v3, v18, v2
	v_cvt_pk_bf16_f32 v3, v3, s0
	ds_write_b16 v101, v3 offset:2080
	v_mul_f32_e32 v3, v19, v2
	v_cvt_pk_bf16_f32 v3, v3, s0
	ds_write_b16 v101, v3 offset:2096
	v_mul_f32_e32 v3, v20, v2
	v_cvt_pk_bf16_f32 v3, v3, s0
	ds_write_b16 v101, v3 offset:2176
	v_mul_f32_e32 v3, v21, v2
	v_cvt_pk_bf16_f32 v3, v3, s0
	ds_write_b16 v101, v3 offset:2192
	v_mul_f32_e32 v3, v22, v2
	v_cvt_pk_bf16_f32 v3, v3, s0
	ds_write_b16 v101, v3 offset:2208
	v_mul_f32_e32 v3, v23, v2
	v_cvt_pk_bf16_f32 v3, v3, s0
	ds_write_b16 v101, v3 offset:2224
	v_mul_f32_e32 v3, v24, v2
	v_cvt_pk_bf16_f32 v3, v3, s0
	ds_write_b16 v101, v3 offset:2304
	v_mul_f32_e32 v3, v25, v2
	v_cvt_pk_bf16_f32 v3, v3, s0
	ds_write_b16 v101, v3 offset:2320
	v_mul_f32_e32 v3, v26, v2
	v_cvt_pk_bf16_f32 v3, v3, s0
	ds_write_b16 v101, v3 offset:2336
	v_mul_f32_e32 v3, v27, v2
	v_cvt_pk_bf16_f32 v3, v3, s0
	ds_write_b16 v101, v3 offset:2352
	v_mul_f32_e32 v3, v28, v2
	v_cvt_pk_bf16_f32 v3, v3, s0
	ds_write_b16 v101, v3 offset:2432
	v_mul_f32_e32 v3, v29, v2
	v_cvt_pk_bf16_f32 v3, v3, s0
	ds_write_b16 v101, v3 offset:2448
	v_mul_f32_e32 v3, v30, v2
	v_mul_f32_e32 v2, v31, v2
	v_cvt_pk_bf16_f32 v3, v3, s0
	v_cvt_pk_bf16_f32 v2, v2, s0
	ds_write_b16 v101, v3 offset:2464
	ds_write_b16 v101, v2 offset:2480
	v_lshlrev_b32_e32 v0, 5, v36
	v_and_b32_e32 v12, 0xe0, v0
	v_lshlrev_b32_e32 v0, 4, v36
	v_and_b32_e32 v0, 0x70, v0
	v_add_u32_e32 v4, 0, v0
	v_ashrrev_i32_e32 v0, 3, v36
	v_and_b32_e32 v5, 0x78, v36
	v_and_b32_e32 v1, 0xffffff00, v36
	v_and_b32_e32 v2, 16, v0
	v_or3_b32 v6, v2, v1, v12
	v_mad_u64_u32 v[0:1], s[4:5], v0, s24, v[4:5]
	ds_write_b16 v101, v9 offset:400
	ds_read_b128 v[104:107], v103
	ds_read_b128 v[108:111], v103 offset:1024
	ds_read_b128 v[112:115], v103 offset:2048
	ds_read_b128 v[116:119], v103 offset:3072
	s_waitcnt lgkmcnt(0)
	global_store_dwordx4 v102, v[104:107], s[98:99]
	global_store_dwordx4 v102, v[108:111], s[98:99] offset:1024
	global_store_dwordx4 v102, v[112:115], s[100:101]
	global_store_dwordx4 v102, v[116:119], s[100:101] offset:1024
	ds_read_b128 v[0:3], v0 offset:35072
	v_ashrrev_i32_e32 v6, 4, v6
	v_mov_b64_e32 v[8:9], s[2:3]
	v_mad_i64_i32 v[6:7], s[2:3], v6, s9, v[8:9]
	v_lshlrev_b32_e32 v34, 1, v5
	v_lshl_add_u64 v[6:7], v[6:7], 0, v[34:35]
	v_add_u32_e32 v13, 0x200, v36
	v_add_co_u32_e32 v10, vcc, s10, v6
	v_ashrrev_i32_e32 v14, 3, v13
	s_nop 0
	v_addc_co_u32_e32 v11, vcc, 0, v7, vcc
	v_mad_u64_u32 v[4:5], s[2:3], v14, s24, v[4:5]
	ds_read_b128 v[4:7], v4 offset:35072
	s_waitcnt lgkmcnt(1)
	global_store_dwordx4 v[10:11], v[0:3], off
	s_nop 1
	v_and_b32_e32 v0, 0xffffff00, v13
	v_and_b32_e32 v1, 16, v14
	v_or3_b32 v0, v0, v1, v12
	v_ashrrev_i32_e32 v0, 4, v0
	v_mad_i64_i32 v[0:1], s[2:3], v0, s9, v[8:9]
	v_lshl_add_u64 v[0:1], v[0:1], 0, v[34:35]
	v_add_co_u32_e32 v0, vcc, 0x1000, v0
	s_nop 1
	v_addc_co_u32_e32 v1, vcc, 0, v1, vcc
	s_waitcnt lgkmcnt(0)
	global_store_dwordx4 v[0:1], v[4:7], off
	s_barrier
	s_cbranch_scc0 .LBB0_417
